# attention queue order: CF units drawn before the shorter B-context units so the phase ends on its shortest units
# speedup vs baseline: 1.0016x; 1.0016x over previous
.LBB0_364:
	s_or_b64 exec, exec, s[0:1]
	v_readlane_b32 s0, v254, 15
	s_waitcnt lgkmcnt(0)
	s_barrier
	v_mov_b32_e32 v0, s0
	ds_read_b32 v0, v0
	s_mov_b64 s[0:1], -1
	s_waitcnt lgkmcnt(0)
	v_readfirstlane_b32 s28, v0
	s_nop 3
	s_add_i32 s2, s28, 0x100
	s_add_i32 s3, s28, 0xffffff80
	s_cmpk_lt_u32 s28, 0x380
	s_cselect_b32 s2, s2, s3
	s_cmpk_lt_u32 s28, 0x300
	s_cselect_b32 s2, s28, s2
	s_cmpk_gt_u32 s28, 0x47f
	s_cselect_b32 s28, s28, s2
	s_cmpk_gt_i32 s28, 0x47f
	s_cbranch_scc1 .LBB0_361
	s_cmp_gt_i32 s28, 31
	s_cbranch_scc0 .LBB0_517
	s_cmpk_gt_u32 s28, 0x9f
	s_cbranch_scc0 .LBB0_499
	s_cmpk_gt_u32 s28, 0xff
	s_cbranch_scc0 .LBB0_490
	s_cmpk_gt_u32 s28, 0x17f
	s_cbranch_scc0 .LBB0_457
	s_cmpk_gt_u32 s28, 0x1ff
	s_cbranch_scc0 .LBB0_441
	s_cmpk_gt_u32 s28, 0x2ff
	s_cbranch_scc0 .LBB0_417
	s_cmpk_gt_u32 s28, 0x3ff
	s_cbranch_scc0 .LBB0_408
	s_cmpk_gt_u32 s28, 0x43f
	s_cbranch_scc0 .LBB0_390
	s_add_i32 s0, s28, 0xfffffbc0
	s_lshr_b32 s21, s0, 2
	s_mov_b32 s0, s91
	s_and_b32 s20, s28, 3
	v_or_b32_e32 v0, s0, v230
	v_cmp_eq_u32_e32 vcc, 0, v0
	s_and_saveexec_b64 s[0:1], vcc
	s_cbranch_execz .LBB0_387
	v_readlane_b32 s4, v254, 59
	s_mov_b32 s64, 0
	s_add_i32 s4, s21, s4
	s_xor_b64 s[2:3], s[64:65], s[62:63]
	s_lshl_b32 s64, s4, 2
	s_lshl_b64 s[4:5], s[64:65], 2
	s_add_u32 s2, s2, s4
	s_addc_u32 s3, s3, s5
	s_lshl_b32 s4, s20, 2
	s_add_u32 s2, s2, s4
	s_addc_u32 s3, s3, 0
	s_add_u32 s2, s2, 0xee3e100
	s_addc_u32 s3, s3, 0
	s_mov_b32 s22, 0x400001
	s_mov_b64 s[4:5], 0
	s_branch .LBB0_380
